# v8 + GEMM3 fused epilogue: the 16 serialized x-quad load/wait round trips of the second half issued together up front (one wait)
# speedup vs baseline: 1.0062x; 1.0062x over previous
.LBB0_266:
	s_or_b64 exec, exec, s[2:3]
	s_add_i32 s2, s28, 0x80
	v_or_b32_e32 v66, s2, v219
	v_add_u32_e32 v74, s30, v66
	v_ashrrev_i32_e32 v75, 31, v74
	v_lshlrev_b64 v[68:69], 12, v[74:75]
	v_lshl_add_u64 v[76:77], v[216:217], 0, v[68:69]
	global_load_dwordx4 v[146:149], v[76:77], off
	global_load_dwordx4 v[150:153], v[76:77], off offset:64
	global_load_dwordx4 v[154:157], v[76:77], off offset:512
	global_load_dwordx4 v[158:161], v[76:77], off offset:576
	v_or_b32_e32 v248, 16, v66
	v_add_u32_e32 v250, s30, v248
	v_ashrrev_i32_e32 v251, 31, v250
	v_lshlrev_b64 v[250:251], 12, v[250:251]
	v_lshl_add_u64 v[250:251], v[216:217], 0, v[250:251]
	global_load_dwordx4 v[162:165], v[250:251], off
	global_load_dwordx4 v[166:169], v[250:251], off offset:64
	global_load_dwordx4 v[170:173], v[250:251], off offset:512
	global_load_dwordx4 v[174:177], v[250:251], off offset:576
	v_or_b32_e32 v248, 32, v66
	v_add_u32_e32 v252, s30, v248
	v_ashrrev_i32_e32 v253, 31, v252
	v_lshlrev_b64 v[252:253], 12, v[252:253]
	v_lshl_add_u64 v[252:253], v[216:217], 0, v[252:253]
	global_load_dwordx4 v[178:181], v[252:253], off
	global_load_dwordx4 v[182:185], v[252:253], off offset:64
	global_load_dwordx4 v[186:189], v[252:253], off offset:512
	global_load_dwordx4 v[190:193], v[252:253], off offset:576
	v_or_b32_e32 v248, 48, v66
	v_add_u32_e32 v254, s30, v248
	v_ashrrev_i32_e32 v255, 31, v254
	v_lshlrev_b64 v[254:255], 12, v[254:255]
	v_lshl_add_u64 v[254:255], v[216:217], 0, v[254:255]
	global_load_dwordx4 v[194:197], v[254:255], off
	global_load_dwordx4 v[198:201], v[254:255], off offset:64
	global_load_dwordx4 v[202:205], v[254:255], off offset:512
	global_load_dwordx4 v[206:209], v[254:255], off offset:576
	s_waitcnt lgkmcnt(0)
	v_add_u32_e32 v67, s28, v219
	v_lshl_add_u32 v67, v67, 2, 0
	ds_read_b32 v78, v67 offset:8704
	v_lshlrev_b64 v[74:75], 10, v[74:75]
	v_lshl_add_u64 v[74:75], v[74:75], 0, v[214:215]
	v_mov_b32_e32 v68, 0x7fc00000
	v_lshl_add_u64 v[74:75], v[74:75], 1, s[0:1]
	s_waitcnt lgkmcnt(0)
	v_pk_mul_f32 v[64:65], v[64:65], v[78:79] op_sel_hi:[1,0]
	v_pk_mul_f32 v[62:63], v[62:63], v[78:79] op_sel_hi:[1,0]
	v_pk_mul_f32 v[60:61], v[60:61], v[78:79] op_sel_hi:[1,0]
	v_pk_mul_f32 v[58:59], v[58:59], v[78:79] op_sel_hi:[1,0]
	v_pk_mul_f32 v[56:57], v[56:57], v[78:79] op_sel_hi:[1,0]
	v_pk_mul_f32 v[54:55], v[54:55], v[78:79] op_sel_hi:[1,0]
	v_pk_mul_f32 v[52:53], v[52:53], v[78:79] op_sel_hi:[1,0]
	v_pk_mul_f32 v[50:51], v[50:51], v[78:79] op_sel_hi:[1,0]
	s_waitcnt vmcnt(0)
	v_pk_fma_f32 v[64:65], v[144:145], v[64:65], v[148:149]
	v_pk_fma_f32 v[62:63], v[142:143], v[62:63], v[146:147]
	v_cndmask_b32_e32 v69, v64, v68, vcc
	v_cndmask_b32_e32 v70, v65, v68, vcc
	v_cndmask_b32_e32 v71, v62, v68, vcc
	v_cndmask_b32_e32 v72, v63, v68, vcc
	v_cvt_pk_bf16_f32 v62, v71, v72
	v_cvt_pk_bf16_f32 v63, v69, v70
	v_mov_b32_e32 v240, v62
	v_mov_b32_e32 v241, v63
	v_mul_f32_e32 v72, v72, v72
	v_mul_f32_e32 v70, v70, v70
	v_fmac_f32_e32 v72, v71, v71
	v_fmac_f32_e32 v70, v69, v69
	v_add_f32_e32 v69, v72, v70
	v_pk_fma_f32 v[60:61], v[136:137], v[60:61], v[152:153]
	v_pk_fma_f32 v[58:59], v[134:135], v[58:59], v[150:151]
	v_cndmask_b32_e32 v62, v60, v68, vcc
	v_cndmask_b32_e32 v63, v61, v68, vcc
	v_cndmask_b32_e32 v64, v58, v68, vcc
	v_cndmask_b32_e32 v65, v59, v68, vcc
	v_cvt_pk_bf16_f32 v58, v64, v65
	v_cvt_pk_bf16_f32 v59, v62, v63
	v_mov_b32_e32 v242, v58
	v_mov_b32_e32 v243, v59
	s_nop 1
	v_permlane32_swap_b32_e32 v240, v242
	v_permlane32_swap_b32_e32 v241, v243
	s_nop 0
	v_permlane16_swap_b32_e32 v240, v242
	v_permlane16_swap_b32_e32 v241, v243
	v_lshl_add_u64 v[236:237], v[74:75], 0, v[238:239]
	global_store_dwordx4 v[236:237], v[240:243], off
	v_mul_f32_e32 v65, v65, v65
	v_mul_f32_e32 v63, v63, v63
	v_fmac_f32_e32 v65, v64, v64
	v_fmac_f32_e32 v63, v62, v62
	v_add_f32_e32 v62, v65, v63
	v_add_f32_e32 v62, v69, v62
	v_pk_fma_f32 v[56:57], v[132:133], v[56:57], v[156:157]
	v_pk_fma_f32 v[54:55], v[130:131], v[54:55], v[154:155]
	v_cndmask_b32_e32 v58, v56, v68, vcc
	v_cndmask_b32_e32 v59, v57, v68, vcc
	v_cndmask_b32_e32 v60, v54, v68, vcc
	v_cndmask_b32_e32 v61, v55, v68, vcc
	v_cvt_pk_bf16_f32 v54, v60, v61
	v_cvt_pk_bf16_f32 v55, v58, v59
	v_mov_b32_e32 v244, v54
	v_mov_b32_e32 v245, v55
	v_mul_f32_e32 v61, v61, v61
	v_mul_f32_e32 v59, v59, v59
	v_fmac_f32_e32 v61, v60, v60
	v_fmac_f32_e32 v59, v58, v58
	v_add_f32_e32 v58, v61, v59
	v_add_f32_e32 v58, v62, v58
	v_pk_fma_f32 v[52:53], v[124:125], v[52:53], v[160:161]
	v_pk_fma_f32 v[50:51], v[122:123], v[50:51], v[158:159]
	v_cndmask_b32_e32 v53, v53, v68, vcc
	v_cndmask_b32_e32 v55, v51, v68, vcc
	v_cndmask_b32_e32 v54, v52, v68, vcc
	v_cndmask_b32_e32 v52, v50, v68, vcc
	v_mul_f32_e32 v50, v55, v55
	v_mul_f32_e32 v51, v53, v53
	v_fmac_f32_e32 v50, v52, v52
	v_fmac_f32_e32 v51, v54, v54
	v_add_f32_e32 v50, v50, v51
	v_add_f32_e32 v50, v58, v50
	ds_bpermute_b32 v51, v1, v50
	v_cvt_pk_bf16_f32 v52, v52, v55
	v_cvt_pk_bf16_f32 v53, v54, v53
	v_mov_b32_e32 v246, v52
	v_mov_b32_e32 v247, v53
	s_nop 1
	v_permlane32_swap_b32_e32 v244, v246
	v_permlane32_swap_b32_e32 v245, v247
	s_nop 0
	v_permlane16_swap_b32_e32 v244, v246
	v_permlane16_swap_b32_e32 v245, v247
	v_lshl_add_u64 v[236:237], v[74:75], 0, v[238:239]
	global_store_dwordx4 v[236:237], v[244:247], off offset:256
	s_waitcnt lgkmcnt(0)
	v_add_f32_e32 v50, v50, v51
	ds_bpermute_b32 v51, v233, v50
	s_and_saveexec_b64 s[2:3], s[4:5]
	s_cbranch_execz .LBB0_268
	v_lshl_add_u32 v52, v66, 4, s31
	s_waitcnt lgkmcnt(0)
	v_add_f32_e32 v50, v50, v51
	ds_write_b32 v52, v50 offset:16384
.LBB0_268:
	s_or_b64 exec, exec, s[2:3]
	v_or_b32_e32 v50, 16, v66
	v_add_u32_e32 v56, s30, v50
	v_ashrrev_i32_e32 v57, 31, v56
	v_lshlrev_b64 v[52:53], 12, v[56:57]
	v_lshl_add_u64 v[58:59], v[216:217], 0, v[52:53]
	ds_read_b32 v60, v67 offset:8768
	v_lshlrev_b64 v[56:57], 10, v[56:57]
	v_lshl_add_u64 v[56:57], v[56:57], 0, v[214:215]
	v_lshl_add_u64 v[56:57], v[56:57], 1, s[0:1]
	s_waitcnt lgkmcnt(0)
	v_pk_mul_f32 v[48:49], v[48:49], v[60:61] op_sel_hi:[1,0]
	v_pk_mul_f32 v[46:47], v[46:47], v[60:61] op_sel_hi:[1,0]
	v_pk_mul_f32 v[44:45], v[44:45], v[60:61] op_sel_hi:[1,0]
	v_pk_mul_f32 v[42:43], v[42:43], v[60:61] op_sel_hi:[1,0]
	v_pk_mul_f32 v[40:41], v[40:41], v[60:61] op_sel_hi:[1,0]
	v_pk_mul_f32 v[38:39], v[38:39], v[60:61] op_sel_hi:[1,0]
	v_pk_mul_f32 v[36:37], v[36:37], v[60:61] op_sel_hi:[1,0]
	v_pk_mul_f32 v[34:35], v[34:35], v[60:61] op_sel_hi:[1,0]
	v_pk_fma_f32 v[48:49], v[144:145], v[48:49], v[164:165]
	v_pk_fma_f32 v[46:47], v[142:143], v[46:47], v[162:163]
	v_cndmask_b32_e32 v51, v48, v68, vcc
	v_cndmask_b32_e32 v52, v49, v68, vcc
	v_cndmask_b32_e32 v53, v46, v68, vcc
	v_cndmask_b32_e32 v54, v47, v68, vcc
	v_cvt_pk_bf16_f32 v46, v53, v54
	v_cvt_pk_bf16_f32 v47, v51, v52
	v_mov_b32_e32 v240, v46
	v_mov_b32_e32 v241, v47
	v_mul_f32_e32 v54, v54, v54
	v_mul_f32_e32 v52, v52, v52
	v_fmac_f32_e32 v54, v53, v53
	v_fmac_f32_e32 v52, v51, v51
	v_add_f32_e32 v51, v54, v52
	v_pk_fma_f32 v[44:45], v[136:137], v[44:45], v[168:169]
	v_pk_fma_f32 v[42:43], v[134:135], v[42:43], v[166:167]
	v_cndmask_b32_e32 v46, v44, v68, vcc
	v_cndmask_b32_e32 v47, v45, v68, vcc
	v_cndmask_b32_e32 v48, v42, v68, vcc
	v_cndmask_b32_e32 v49, v43, v68, vcc
	v_cvt_pk_bf16_f32 v42, v48, v49
	v_cvt_pk_bf16_f32 v43, v46, v47
	v_mov_b32_e32 v242, v42
	v_mov_b32_e32 v243, v43
	s_nop 1
	v_permlane32_swap_b32_e32 v240, v242
	v_permlane32_swap_b32_e32 v241, v243
	s_nop 0
	v_permlane16_swap_b32_e32 v240, v242
	v_permlane16_swap_b32_e32 v241, v243
	v_lshl_add_u64 v[236:237], v[56:57], 0, v[238:239]
	global_store_dwordx4 v[236:237], v[240:243], off
	v_mul_f32_e32 v49, v49, v49
	v_mul_f32_e32 v47, v47, v47
	v_fmac_f32_e32 v49, v48, v48
	v_fmac_f32_e32 v47, v46, v46
	v_add_f32_e32 v46, v49, v47
	v_add_f32_e32 v46, v51, v46
	v_pk_fma_f32 v[40:41], v[132:133], v[40:41], v[172:173]
	v_pk_fma_f32 v[38:39], v[130:131], v[38:39], v[170:171]
	v_cndmask_b32_e32 v42, v40, v68, vcc
	v_cndmask_b32_e32 v43, v41, v68, vcc
	v_cndmask_b32_e32 v44, v38, v68, vcc
	v_cndmask_b32_e32 v45, v39, v68, vcc
	v_cvt_pk_bf16_f32 v38, v44, v45
	v_cvt_pk_bf16_f32 v39, v42, v43
	v_mov_b32_e32 v244, v38
	v_mov_b32_e32 v245, v39
	v_mul_f32_e32 v45, v45, v45
	v_mul_f32_e32 v43, v43, v43
	v_fmac_f32_e32 v45, v44, v44
	v_fmac_f32_e32 v43, v42, v42
	v_add_f32_e32 v42, v45, v43
	v_add_f32_e32 v42, v46, v42
	v_pk_fma_f32 v[36:37], v[124:125], v[36:37], v[176:177]
	v_pk_fma_f32 v[34:35], v[122:123], v[34:35], v[174:175]
	v_cndmask_b32_e32 v37, v37, v68, vcc
	v_cndmask_b32_e32 v39, v35, v68, vcc
	v_cndmask_b32_e32 v38, v36, v68, vcc
	v_cndmask_b32_e32 v36, v34, v68, vcc
	v_mul_f32_e32 v34, v39, v39
	v_mul_f32_e32 v35, v37, v37
	v_fmac_f32_e32 v34, v36, v36
	v_fmac_f32_e32 v35, v38, v38
	v_add_f32_e32 v34, v34, v35
	v_add_f32_e32 v34, v42, v34
	ds_bpermute_b32 v35, v1, v34
	v_cvt_pk_bf16_f32 v36, v36, v39
	v_cvt_pk_bf16_f32 v37, v38, v37
	v_mov_b32_e32 v246, v36
	v_mov_b32_e32 v247, v37
	s_nop 1
	v_permlane32_swap_b32_e32 v244, v246
	v_permlane32_swap_b32_e32 v245, v247
	s_nop 0
	v_permlane16_swap_b32_e32 v244, v246
	v_permlane16_swap_b32_e32 v245, v247
	v_lshl_add_u64 v[236:237], v[56:57], 0, v[238:239]
	global_store_dwordx4 v[236:237], v[244:247], off offset:256
	s_waitcnt lgkmcnt(0)
	v_add_f32_e32 v34, v34, v35
	ds_bpermute_b32 v35, v233, v34
	s_and_saveexec_b64 s[2:3], s[4:5]
	s_cbranch_execz .LBB0_270
	v_lshl_add_u32 v36, v50, 4, s31
	s_waitcnt lgkmcnt(0)
	v_add_f32_e32 v34, v34, v35
	ds_write_b32 v36, v34 offset:16384
.LBB0_270:
	s_or_b64 exec, exec, s[2:3]
	s_waitcnt lgkmcnt(0)
	v_or_b32_e32 v35, 32, v66
	v_add_u32_e32 v40, s30, v35
	v_ashrrev_i32_e32 v41, 31, v40
	v_lshlrev_b64 v[36:37], 12, v[40:41]
	v_lshl_add_u64 v[42:43], v[216:217], 0, v[36:37]
	ds_read_b32 v44, v210 offset:8832
	v_lshlrev_b64 v[40:41], 10, v[40:41]
	v_lshl_add_u64 v[40:41], v[40:41], 0, v[214:215]
	v_mov_b32_e32 v34, 0x7fc00000
	v_lshl_add_u64 v[40:41], v[40:41], 1, s[0:1]
	s_waitcnt lgkmcnt(0)
	v_pk_mul_f32 v[32:33], v[32:33], v[44:45] op_sel_hi:[1,0]
	v_pk_mul_f32 v[30:31], v[30:31], v[44:45] op_sel_hi:[1,0]
	v_pk_mul_f32 v[28:29], v[28:29], v[44:45] op_sel_hi:[1,0]
	v_pk_mul_f32 v[26:27], v[26:27], v[44:45] op_sel_hi:[1,0]
	v_pk_mul_f32 v[24:25], v[24:25], v[44:45] op_sel_hi:[1,0]
	v_pk_mul_f32 v[22:23], v[22:23], v[44:45] op_sel_hi:[1,0]
	v_pk_mul_f32 v[20:21], v[20:21], v[44:45] op_sel_hi:[1,0]
	v_pk_mul_f32 v[18:19], v[18:19], v[44:45] op_sel_hi:[1,0]
	v_pk_fma_f32 v[32:33], v[144:145], v[32:33], v[180:181]
	v_pk_fma_f32 v[30:31], v[142:143], v[30:31], v[178:179]
	v_cndmask_b32_e32 v36, v32, v34, vcc
	v_cndmask_b32_e32 v37, v33, v34, vcc
	v_cndmask_b32_e32 v38, v30, v34, vcc
	v_cndmask_b32_e32 v39, v31, v34, vcc
	v_cvt_pk_bf16_f32 v30, v38, v39
	v_cvt_pk_bf16_f32 v31, v36, v37
	v_mov_b32_e32 v240, v30
	v_mov_b32_e32 v241, v31
	v_mul_f32_e32 v39, v39, v39
	v_mul_f32_e32 v37, v37, v37
	v_fmac_f32_e32 v39, v38, v38
	v_fmac_f32_e32 v37, v36, v36
	v_add_f32_e32 v36, v39, v37
	v_pk_fma_f32 v[28:29], v[136:137], v[28:29], v[184:185]
	v_pk_fma_f32 v[26:27], v[134:135], v[26:27], v[182:183]
	v_cndmask_b32_e32 v30, v28, v34, vcc
	v_cndmask_b32_e32 v31, v29, v34, vcc
	v_cndmask_b32_e32 v32, v26, v34, vcc
	v_cndmask_b32_e32 v33, v27, v34, vcc
	v_cvt_pk_bf16_f32 v26, v32, v33
	v_cvt_pk_bf16_f32 v27, v30, v31
	v_mov_b32_e32 v242, v26
	v_mov_b32_e32 v243, v27
	s_nop 1
	v_permlane32_swap_b32_e32 v240, v242
	v_permlane32_swap_b32_e32 v241, v243
	s_nop 0
	v_permlane16_swap_b32_e32 v240, v242
	v_permlane16_swap_b32_e32 v241, v243
	v_lshl_add_u64 v[236:237], v[40:41], 0, v[238:239]
	global_store_dwordx4 v[236:237], v[240:243], off
	v_mul_f32_e32 v33, v33, v33
	v_mul_f32_e32 v31, v31, v31
	v_fmac_f32_e32 v33, v32, v32
	v_fmac_f32_e32 v31, v30, v30
	v_add_f32_e32 v30, v33, v31
	v_add_f32_e32 v30, v36, v30
	v_pk_fma_f32 v[24:25], v[132:133], v[24:25], v[188:189]
	v_pk_fma_f32 v[22:23], v[130:131], v[22:23], v[186:187]
	v_cndmask_b32_e32 v26, v24, v34, vcc
	v_cndmask_b32_e32 v27, v25, v34, vcc
	v_cndmask_b32_e32 v28, v22, v34, vcc
	v_cndmask_b32_e32 v29, v23, v34, vcc
	v_cvt_pk_bf16_f32 v22, v28, v29
	v_cvt_pk_bf16_f32 v23, v26, v27
	v_mov_b32_e32 v244, v22
	v_mov_b32_e32 v245, v23
	v_mul_f32_e32 v29, v29, v29
	v_mul_f32_e32 v27, v27, v27
	v_fmac_f32_e32 v29, v28, v28
	v_fmac_f32_e32 v27, v26, v26
	v_add_f32_e32 v26, v29, v27
	v_add_f32_e32 v26, v30, v26
	v_pk_fma_f32 v[20:21], v[124:125], v[20:21], v[192:193]
	v_pk_fma_f32 v[18:19], v[122:123], v[18:19], v[190:191]
	v_cndmask_b32_e32 v21, v21, v34, vcc
	v_cndmask_b32_e32 v23, v19, v34, vcc
	v_cndmask_b32_e32 v22, v20, v34, vcc
	v_cndmask_b32_e32 v20, v18, v34, vcc
	v_mul_f32_e32 v18, v23, v23
	v_mul_f32_e32 v19, v21, v21
	v_fmac_f32_e32 v18, v20, v20
	v_fmac_f32_e32 v19, v22, v22
	v_add_f32_e32 v18, v18, v19
	v_add_f32_e32 v18, v26, v18
	ds_bpermute_b32 v19, v1, v18
	v_cvt_pk_bf16_f32 v20, v20, v23
	v_cvt_pk_bf16_f32 v21, v22, v21
	v_mov_b32_e32 v246, v20
	v_mov_b32_e32 v247, v21
	s_nop 1
	v_permlane32_swap_b32_e32 v244, v246
	v_permlane32_swap_b32_e32 v245, v247
	s_nop 0
	v_permlane16_swap_b32_e32 v244, v246
	v_permlane16_swap_b32_e32 v245, v247
	v_lshl_add_u64 v[236:237], v[40:41], 0, v[238:239]
	global_store_dwordx4 v[236:237], v[244:247], off offset:256
	s_waitcnt lgkmcnt(0)
	v_add_f32_e32 v18, v18, v19
	ds_bpermute_b32 v19, v233, v18
	s_and_saveexec_b64 s[2:3], s[4:5]
	s_cbranch_execz .LBB0_272
	v_lshl_add_u32 v20, v35, 4, s31
	s_waitcnt lgkmcnt(0)
	v_add_f32_e32 v18, v18, v19
	ds_write_b32 v20, v18 offset:16384
.LBB0_272:
	s_or_b64 exec, exec, s[2:3]
	v_or_b32_e32 v18, 48, v66
	v_add_u32_e32 v24, s30, v18
	v_ashrrev_i32_e32 v25, 31, v24
	v_lshlrev_b64 v[20:21], 12, v[24:25]
	v_lshl_add_u64 v[26:27], v[216:217], 0, v[20:21]
	ds_read_b32 v28, v67 offset:8896
	v_lshlrev_b64 v[24:25], 10, v[24:25]
	v_lshl_add_u64 v[24:25], v[24:25], 0, v[214:215]
	v_lshl_add_u64 v[24:25], v[24:25], 1, s[0:1]
	s_waitcnt lgkmcnt(0)
	v_pk_mul_f32 v[16:17], v[16:17], v[28:29] op_sel_hi:[1,0]
	v_pk_mul_f32 v[14:15], v[14:15], v[28:29] op_sel_hi:[1,0]
	v_pk_mul_f32 v[12:13], v[12:13], v[28:29] op_sel_hi:[1,0]
	v_pk_mul_f32 v[10:11], v[10:11], v[28:29] op_sel_hi:[1,0]
	v_pk_mul_f32 v[8:9], v[8:9], v[28:29] op_sel_hi:[1,0]
	v_pk_mul_f32 v[6:7], v[6:7], v[28:29] op_sel_hi:[1,0]
	v_pk_mul_f32 v[4:5], v[4:5], v[28:29] op_sel_hi:[1,0]
	v_pk_mul_f32 v[2:3], v[2:3], v[28:29] op_sel_hi:[1,0]
	v_pk_fma_f32 v[16:17], v[144:145], v[16:17], v[196:197]
	v_pk_fma_f32 v[14:15], v[142:143], v[14:15], v[194:195]
	v_cndmask_b32_e32 v19, v16, v34, vcc
	v_cndmask_b32_e32 v20, v17, v34, vcc
	v_cndmask_b32_e32 v21, v14, v34, vcc
	v_cndmask_b32_e32 v22, v15, v34, vcc
	v_cvt_pk_bf16_f32 v14, v21, v22
	v_cvt_pk_bf16_f32 v15, v19, v20
	v_mov_b32_e32 v240, v14
	v_mov_b32_e32 v241, v15
	v_mul_f32_e32 v22, v22, v22
	v_mul_f32_e32 v20, v20, v20
	v_fmac_f32_e32 v22, v21, v21
	v_fmac_f32_e32 v20, v19, v19
	v_add_f32_e32 v19, v22, v20
	v_pk_fma_f32 v[12:13], v[136:137], v[12:13], v[200:201]
	v_pk_fma_f32 v[10:11], v[134:135], v[10:11], v[198:199]
	v_cndmask_b32_e32 v14, v12, v34, vcc
	v_cndmask_b32_e32 v15, v13, v34, vcc
	v_cndmask_b32_e32 v16, v10, v34, vcc
	v_cndmask_b32_e32 v17, v11, v34, vcc
	v_cvt_pk_bf16_f32 v10, v16, v17
	v_cvt_pk_bf16_f32 v11, v14, v15
	v_mov_b32_e32 v242, v10
	v_mov_b32_e32 v243, v11
	s_nop 1
	v_permlane32_swap_b32_e32 v240, v242
	v_permlane32_swap_b32_e32 v241, v243
	s_nop 0
	v_permlane16_swap_b32_e32 v240, v242
	v_permlane16_swap_b32_e32 v241, v243
	v_lshl_add_u64 v[236:237], v[24:25], 0, v[238:239]
	global_store_dwordx4 v[236:237], v[240:243], off
	v_mul_f32_e32 v17, v17, v17
	v_mul_f32_e32 v15, v15, v15
	v_fmac_f32_e32 v17, v16, v16
	v_fmac_f32_e32 v15, v14, v14
	v_add_f32_e32 v14, v17, v15
	v_add_f32_e32 v14, v19, v14
	v_pk_fma_f32 v[8:9], v[132:133], v[8:9], v[204:205]
	v_pk_fma_f32 v[6:7], v[130:131], v[6:7], v[202:203]
	v_cndmask_b32_e32 v10, v8, v34, vcc
	v_cndmask_b32_e32 v11, v9, v34, vcc
	v_cndmask_b32_e32 v12, v6, v34, vcc
	v_cndmask_b32_e32 v13, v7, v34, vcc
	v_cvt_pk_bf16_f32 v6, v12, v13
	v_cvt_pk_bf16_f32 v7, v10, v11
	v_mov_b32_e32 v244, v6
	v_mov_b32_e32 v245, v7
	v_mul_f32_e32 v13, v13, v13
	v_mul_f32_e32 v11, v11, v11
	v_fmac_f32_e32 v13, v12, v12
	v_fmac_f32_e32 v11, v10, v10
	v_add_f32_e32 v10, v13, v11
	v_add_f32_e32 v10, v14, v10
	v_pk_fma_f32 v[4:5], v[124:125], v[4:5], v[208:209]
	v_pk_fma_f32 v[2:3], v[122:123], v[2:3], v[206:207]
	v_cndmask_b32_e32 v5, v5, v34, vcc
	v_cndmask_b32_e32 v7, v3, v34, vcc
	v_cndmask_b32_e32 v6, v4, v34, vcc
	v_cndmask_b32_e32 v4, v2, v34, vcc
	v_mul_f32_e32 v2, v7, v7
	v_mul_f32_e32 v3, v5, v5
	v_fmac_f32_e32 v2, v4, v4
	v_fmac_f32_e32 v3, v6, v6
	v_add_f32_e32 v2, v2, v3
	v_add_f32_e32 v2, v10, v2
	ds_bpermute_b32 v3, v1, v2
	v_cvt_pk_bf16_f32 v4, v4, v7
	v_cvt_pk_bf16_f32 v5, v6, v5
	v_mov_b32_e32 v246, v4
	v_mov_b32_e32 v247, v5
	s_nop 1
	v_permlane32_swap_b32_e32 v244, v246
	v_permlane32_swap_b32_e32 v245, v247
	s_nop 0
	v_permlane16_swap_b32_e32 v244, v246
	v_permlane16_swap_b32_e32 v245, v247
	v_lshl_add_u64 v[236:237], v[24:25], 0, v[238:239]
	global_store_dwordx4 v[236:237], v[244:247], off offset:256
	s_waitcnt lgkmcnt(0)
	v_add_f32_e32 v2, v2, v3
	ds_bpermute_b32 v3, v233, v2
	s_and_saveexec_b64 s[0:1], s[4:5]
	s_cbranch_execz .LBB0_274
	v_lshl_add_u32 v4, v18, 4, s31
	s_waitcnt lgkmcnt(0)
	v_add_f32_e32 v2, v2, v3
	ds_write_b32 v4, v2 offset:16384
